# attention: K-tile staging (global loads + LDS writes) moved from the score waves to the value waves, tile it+1 staged during interval it in two halves
# speedup vs baseline: 1.0225x; 1.0075x over previous
.LBB0_382:
	s_andn2_b64 vcc, exec, s[4:5]
	s_cbranch_vccnz .LBB0_418
	s_and_b64 s[4:5], s[68:69], exec
	v_readlane_b32 s4, v255, 36
	s_cselect_b32 s3, 0x100, 0
	s_and_b32 s4, s4, 56
	s_and_b32 s5, s2, 0xffffffc0
	s_or_b32 s4, s4, s5
	s_bfe_u32 s5, s2, 0x30003
	s_or_b32 s20, s3, 0x800
	s_or_b32 s4, s4, s5
	s_cmpk_eq_i32 s76, 0x100
	s_cselect_b32 s21, s4, s2
	s_cmp_ge_i32 s21, s20
	s_cbranch_scc1 .LBB0_418
	s_add_u32 s6, s54, 0x11f80000
	s_addc_u32 s7, s55, 0
	s_lshl_b32 s22, s76, 1
	s_and_b64 s[4:5], s[68:69], exec
	s_cselect_b32 s23, 8, 0
	s_abs_i32 s24, s76
	s_waitcnt vmcnt(0)
	v_cvt_f32_u32_e32 v9, s24
	v_lshrrev_b32_e32 v5, 5, v158
	v_lshrrev_b32_e32 v0, 2, v219
	v_lshl_or_b32 v0, v5, 2, v0
	v_rcp_iflag_f32_e32 v9, v9
	v_mul_u32_u24_e32 v6, 0x148, v0
	v_lshlrev_b32_e32 v0, 2, v218
	v_and_b32_e32 v8, 12, v0
	v_mul_f32_e32 v9, 0x4f7ffffe, v9
	v_cvt_u32_f32_e32 v9, v9
	v_and_b32_e32 v0, 0xff, v160
	v_ashrrev_i32_e32 v0, 2, v0
	s_movk_i32 s4, 0x148
	s_sub_i32 s8, 0, s24
	v_readfirstlane_b32 s9, v9
	v_mul_lo_u32 v2, v0, s4
	v_and_b32_e32 v3, 3, v218
	s_movk_i32 s4, 0x50
	s_mul_i32 s8, s8, s9
	v_mad_u32_u24 v2, v3, s4, v2
	v_lshlrev_b32_e32 v0, 3, v0
	s_mul_hi_u32 s8, s9, s8
	v_and_b32_e32 v7, 16, v218
	v_lshlrev_b32_e32 v169, 4, v158
	v_lshlrev_b32_e32 v170, 1, v2
	v_sub_u32_e32 v2, v2, v0
	s_add_i32 s26, s9, s8
	v_readlane_b32 s8, v255, 29
	v_and_b32_e32 v4, 31, v218
	v_ashrrev_i32_e32 v3, 31, v2
	v_lshlrev_b32_e32 v0, 3, v5
	v_lshlrev_b32_e32 v5, 4, v5
	v_add_u32_e32 v172, s8, v169
	v_add3_u32 v6, v6, v7, v8
	s_movk_i32 s8, 0x290
	v_bfe_u32 v161, v218, 4, 1
	v_lshlrev_b32_e32 v168, 2, v4
	v_cmp_gt_u32_e64 s[4:5], 32, v158
	v_lshlrev_b32_e32 v171, 2, v158
	s_ashr_i32 s25, s76, 31
	v_lshl_add_u32 v173, v6, 1, 0
	v_mad_u32_u24 v174, v4, s8, v5
	v_lshlrev_b64 v[162:163], 1, v[2:3]
	v_lshlrev_b32_e32 v164, 1, v0
	s_branch .LBB0_387

.LBB0_395:
	s_cmp_lt_i32 s27, 0
	v_mov_b32_e32 v0, v1
	v_mov_b32_e32 v2, v1
	v_mov_b32_e32 v3, v1
	v_mov_b32_e32 v4, v1
	v_mov_b32_e32 v5, v1
	v_mov_b32_e32 v6, v1
	v_mov_b32_e32 v7, v1
	v_mov_b32_e32 v8, v1
	v_mov_b32_e32 v9, v1
	v_mov_b32_e32 v10, v1
	v_mov_b32_e32 v11, v1
	v_mov_b32_e32 v12, v1
	v_mov_b32_e32 v13, v1
	v_mov_b32_e32 v14, v1
	v_mov_b32_e32 v15, v1
	v_lshl_add_u64 v[252:253], s[16:17], 0, v[162:163]
	global_load_dwordx4 v[16:19], v[252:253], off
	global_load_dwordx4 v[20:23], v[252:253], off offset:16
	global_load_dwordx4 v[24:27], v[252:253], off offset:32
	global_load_dwordx4 v[28:31], v[252:253], off offset:48
	global_load_dwordx4 v[32:35], v[252:253], off offset:64
	global_load_dwordx4 v[36:39], v[252:253], off offset:80
	global_load_dwordx4 v[40:43], v[252:253], off offset:96
	global_load_dwordx4 v[44:47], v[252:253], off offset:112
	global_load_dwordx4 v[48:51], v[252:253], off offset:128
	global_load_dwordx4 v[52:55], v[252:253], off offset:144
	s_waitcnt vmcnt(0)
	ds_write_b128 v170, v[16:19]
	ds_write_b128 v170, v[20:23] offset:16
	ds_write_b128 v170, v[24:27] offset:32
	ds_write_b128 v170, v[28:31] offset:48
	ds_write_b128 v170, v[32:35] offset:64
	ds_write_b128 v170, v[36:39] offset:80
	ds_write_b128 v170, v[40:43] offset:96
	ds_write_b128 v170, v[44:47] offset:112
	ds_write_b128 v170, v[48:51] offset:128
	ds_write_b128 v170, v[52:55] offset:144
	s_mov_b64 s[8:9], 0xa000
	v_lshl_add_u64 v[252:253], v[252:253], 0, s[8:9]
	s_waitcnt lgkmcnt(0)
	s_barrier
	s_cbranch_scc1 .LBB0_403
	v_mov_b64_e32 v[30:31], v[14:15]
	s_waitcnt vmcnt(26)
	v_mov_b64_e32 v[46:47], v[14:15]
	s_waitcnt vmcnt(22)
	v_mov_b64_e32 v[62:63], v[14:15]
	s_waitcnt vmcnt(18)
	v_mov_b64_e32 v[78:79], v[14:15]
	s_waitcnt vmcnt(14)
	v_mov_b64_e32 v[94:95], v[14:15]
	s_waitcnt vmcnt(10)
	v_mov_b64_e32 v[110:111], v[14:15]
	s_waitcnt vmcnt(6)
	v_mov_b64_e32 v[126:127], v[14:15]
	s_waitcnt vmcnt(2)
	v_mov_b64_e32 v[142:143], v[14:15]
	s_mov_b32 s30, 0
	s_mov_b32 s18, -4
	s_mov_b32 s19, -1
	v_mov_b32_e32 v144, v173
	v_mov_b64_e32 v[28:29], v[12:13]
	v_mov_b64_e32 v[26:27], v[10:11]
	v_mov_b64_e32 v[24:25], v[8:9]
	v_mov_b64_e32 v[22:23], v[6:7]
	v_mov_b64_e32 v[20:21], v[4:5]
	v_mov_b64_e32 v[18:19], v[2:3]
	v_mov_b64_e32 v[16:17], v[0:1]
	v_mov_b64_e32 v[44:45], v[12:13]
	v_mov_b64_e32 v[42:43], v[10:11]
	v_mov_b64_e32 v[40:41], v[8:9]
	v_mov_b64_e32 v[38:39], v[6:7]
	v_mov_b64_e32 v[36:37], v[4:5]
	v_mov_b64_e32 v[34:35], v[2:3]
	v_mov_b64_e32 v[32:33], v[0:1]
	v_mov_b64_e32 v[60:61], v[12:13]
	v_mov_b64_e32 v[58:59], v[10:11]
	v_mov_b64_e32 v[56:57], v[8:9]
	v_mov_b64_e32 v[54:55], v[6:7]
	v_mov_b64_e32 v[52:53], v[4:5]
	v_mov_b64_e32 v[50:51], v[2:3]
	v_mov_b64_e32 v[48:49], v[0:1]
	v_mov_b64_e32 v[76:77], v[12:13]
	v_mov_b64_e32 v[74:75], v[10:11]
	v_mov_b64_e32 v[72:73], v[8:9]
	v_mov_b64_e32 v[70:71], v[6:7]
	v_mov_b64_e32 v[68:69], v[4:5]
	v_mov_b64_e32 v[66:67], v[2:3]
	v_mov_b64_e32 v[64:65], v[0:1]
	v_mov_b64_e32 v[92:93], v[12:13]
	v_mov_b64_e32 v[90:91], v[10:11]
	v_mov_b64_e32 v[88:89], v[8:9]
	v_mov_b64_e32 v[86:87], v[6:7]
	v_mov_b64_e32 v[84:85], v[4:5]
	v_mov_b64_e32 v[82:83], v[2:3]
	v_mov_b64_e32 v[80:81], v[0:1]
	v_mov_b64_e32 v[108:109], v[12:13]
	v_mov_b64_e32 v[106:107], v[10:11]
	v_mov_b64_e32 v[104:105], v[8:9]
	v_mov_b64_e32 v[102:103], v[6:7]
	v_mov_b64_e32 v[100:101], v[4:5]
	v_mov_b64_e32 v[98:99], v[2:3]
	v_mov_b64_e32 v[96:97], v[0:1]
	v_mov_b64_e32 v[124:125], v[12:13]
	v_mov_b64_e32 v[122:123], v[10:11]
	v_mov_b64_e32 v[120:121], v[8:9]
	v_mov_b64_e32 v[118:119], v[6:7]
	v_mov_b64_e32 v[116:117], v[4:5]
	v_mov_b64_e32 v[114:115], v[2:3]
	v_mov_b64_e32 v[112:113], v[0:1]
	v_mov_b64_e32 v[140:141], v[12:13]
	v_mov_b64_e32 v[138:139], v[10:11]
	v_mov_b64_e32 v[136:137], v[8:9]
	v_mov_b64_e32 v[134:135], v[6:7]
	v_mov_b64_e32 v[132:133], v[4:5]
	v_mov_b64_e32 v[130:131], v[2:3]
	v_mov_b64_e32 v[128:129], v[0:1]
	s_cmp_eq_u32 s30, 0
	s_cbranch_scc1 .Lav_stage0
.LBB0_397:
	s_add_i32 s8, s19, 2
	s_mul_hi_u32 s9, s8, 0xaaaaaaab
	s_lshr_b32 s9, s9, 1
	s_mul_i32 s9, s9, 3
	s_sub_i32 s8, s8, s9
	s_mul_i32 s8, s8, 0xa400
	v_add_u32_e32 v145, s8, v170
	global_load_dwordx4 v[4:7], v[252:253], off
	global_load_dwordx4 v[8:11], v[252:253], off offset:16
	global_load_dwordx4 v[12:15], v[252:253], off offset:32
	global_load_dwordx4 v[146:149], v[252:253], off offset:48
	global_load_dwordx4 v[150:153], v[252:253], off offset:64
	s_lshl_b32 s8, s30, 2
	s_add_i32 s8, s8, -4
	s_and_b32 s8, s8, 4
	v_readlane_b32 s9, v255, 28
	s_or_b32 s8, s8, s9
	s_mulk_i32 s8, 0x1080
	s_add_i32 s8, s8, 0x1ec00
	v_add_u32_e32 v0, s8, v168
	ds_read_b32 v0, v0 offset:4096
	s_bfe_u32 s8, s18, 0x10002
	s_mulk_i32 s8, 0x4200
	s_add_i32 s8, s8, 0xfffffc00
	v_add_u32_e32 v2, s8, v172
	s_mul_hi_u32 s8, s19, 0xaaaaaaab
	s_lshr_b32 s8, s8, 1
	s_mul_i32 s8, s8, 0xfffe1400
	s_add_i32 s8, s8, 0xffff5c00
	v_add_u32_e32 v3, s8, v144
	ds_read_b128 v[176:179], v2
	ds_read_b128 v[180:183], v2 offset:1024
	ds_read_b128 v[184:187], v2 offset:2048
	ds_read_b128 v[188:191], v2 offset:3072
	ds_read_b64_tr_b16 v[220:221], v3
	ds_read_b64_tr_b16 v[222:223], v3 offset:5248
	ds_read_b64_tr_b16 v[224:225], v3 offset:64
	ds_read_b64_tr_b16 v[226:227], v3 offset:5312
	ds_read_b64_tr_b16 v[228:229], v3 offset:128
	ds_read_b64_tr_b16 v[230:231], v3 offset:5376
	ds_read_b64_tr_b16 v[232:233], v3 offset:192
	ds_read_b64_tr_b16 v[234:235], v3 offset:5440
	ds_read_b64_tr_b16 v[236:237], v3 offset:256
	ds_read_b64_tr_b16 v[238:239], v3 offset:5504
	s_waitcnt lgkmcnt(14)
	v_cmp_neq_f32_e32 vcc, 1.0, v0
	s_cbranch_vccz .Lav_noscale
	v_pk_mul_f32 v[142:143], v[0:1], v[142:143] op_sel_hi:[0,1]
	v_pk_mul_f32 v[140:141], v[0:1], v[140:141] op_sel_hi:[0,1]
	v_pk_mul_f32 v[138:139], v[0:1], v[138:139] op_sel_hi:[0,1]
	v_pk_mul_f32 v[136:137], v[0:1], v[136:137] op_sel_hi:[0,1]
	v_pk_mul_f32 v[134:135], v[0:1], v[134:135] op_sel_hi:[0,1]
	v_pk_mul_f32 v[132:133], v[0:1], v[132:133] op_sel_hi:[0,1]
	v_pk_mul_f32 v[130:131], v[0:1], v[130:131] op_sel_hi:[0,1]
	v_pk_mul_f32 v[128:129], v[0:1], v[128:129] op_sel_hi:[0,1]
	v_pk_mul_f32 v[126:127], v[0:1], v[126:127] op_sel_hi:[0,1]
	v_pk_mul_f32 v[124:125], v[0:1], v[124:125] op_sel_hi:[0,1]
	v_pk_mul_f32 v[122:123], v[0:1], v[122:123] op_sel_hi:[0,1]
	v_pk_mul_f32 v[120:121], v[0:1], v[120:121] op_sel_hi:[0,1]
	v_pk_mul_f32 v[118:119], v[0:1], v[118:119] op_sel_hi:[0,1]
	v_pk_mul_f32 v[116:117], v[0:1], v[116:117] op_sel_hi:[0,1]
	v_pk_mul_f32 v[114:115], v[0:1], v[114:115] op_sel_hi:[0,1]
	v_pk_mul_f32 v[112:113], v[0:1], v[112:113] op_sel_hi:[0,1]
	v_pk_mul_f32 v[110:111], v[0:1], v[110:111] op_sel_hi:[0,1]
	v_pk_mul_f32 v[108:109], v[0:1], v[108:109] op_sel_hi:[0,1]
	v_pk_mul_f32 v[106:107], v[0:1], v[106:107] op_sel_hi:[0,1]
	v_pk_mul_f32 v[104:105], v[0:1], v[104:105] op_sel_hi:[0,1]
	v_pk_mul_f32 v[102:103], v[0:1], v[102:103] op_sel_hi:[0,1]
	v_pk_mul_f32 v[100:101], v[0:1], v[100:101] op_sel_hi:[0,1]
	v_pk_mul_f32 v[98:99], v[0:1], v[98:99] op_sel_hi:[0,1]
	v_pk_mul_f32 v[96:97], v[0:1], v[96:97] op_sel_hi:[0,1]
	v_pk_mul_f32 v[94:95], v[0:1], v[94:95] op_sel_hi:[0,1]
	v_pk_mul_f32 v[92:93], v[0:1], v[92:93] op_sel_hi:[0,1]
	v_pk_mul_f32 v[90:91], v[0:1], v[90:91] op_sel_hi:[0,1]
	v_pk_mul_f32 v[88:89], v[0:1], v[88:89] op_sel_hi:[0,1]
	v_pk_mul_f32 v[86:87], v[0:1], v[86:87] op_sel_hi:[0,1]
	v_pk_mul_f32 v[84:85], v[0:1], v[84:85] op_sel_hi:[0,1]
	v_pk_mul_f32 v[82:83], v[0:1], v[82:83] op_sel_hi:[0,1]
	v_pk_mul_f32 v[80:81], v[0:1], v[80:81] op_sel_hi:[0,1]
	v_pk_mul_f32 v[78:79], v[0:1], v[78:79] op_sel_hi:[0,1]
	v_pk_mul_f32 v[76:77], v[0:1], v[76:77] op_sel_hi:[0,1]
	v_pk_mul_f32 v[74:75], v[0:1], v[74:75] op_sel_hi:[0,1]
	v_pk_mul_f32 v[72:73], v[0:1], v[72:73] op_sel_hi:[0,1]
	v_pk_mul_f32 v[70:71], v[0:1], v[70:71] op_sel_hi:[0,1]
	v_pk_mul_f32 v[68:69], v[0:1], v[68:69] op_sel_hi:[0,1]
	v_pk_mul_f32 v[66:67], v[0:1], v[66:67] op_sel_hi:[0,1]
	v_pk_mul_f32 v[64:65], v[0:1], v[64:65] op_sel_hi:[0,1]
	v_pk_mul_f32 v[62:63], v[0:1], v[62:63] op_sel_hi:[0,1]
	v_pk_mul_f32 v[60:61], v[0:1], v[60:61] op_sel_hi:[0,1]
	v_pk_mul_f32 v[58:59], v[0:1], v[58:59] op_sel_hi:[0,1]
	v_pk_mul_f32 v[56:57], v[0:1], v[56:57] op_sel_hi:[0,1]
	v_pk_mul_f32 v[54:55], v[0:1], v[54:55] op_sel_hi:[0,1]
	v_pk_mul_f32 v[52:53], v[0:1], v[52:53] op_sel_hi:[0,1]
	v_pk_mul_f32 v[50:51], v[0:1], v[50:51] op_sel_hi:[0,1]
	v_pk_mul_f32 v[48:49], v[0:1], v[48:49] op_sel_hi:[0,1]
	v_pk_mul_f32 v[46:47], v[0:1], v[46:47] op_sel_hi:[0,1]
	v_pk_mul_f32 v[44:45], v[0:1], v[44:45] op_sel_hi:[0,1]
	v_pk_mul_f32 v[42:43], v[0:1], v[42:43] op_sel_hi:[0,1]
	v_pk_mul_f32 v[40:41], v[0:1], v[40:41] op_sel_hi:[0,1]
	v_pk_mul_f32 v[38:39], v[0:1], v[38:39] op_sel_hi:[0,1]
	v_pk_mul_f32 v[36:37], v[0:1], v[36:37] op_sel_hi:[0,1]
	v_pk_mul_f32 v[34:35], v[0:1], v[34:35] op_sel_hi:[0,1]
	v_pk_mul_f32 v[32:33], v[0:1], v[32:33] op_sel_hi:[0,1]
	v_pk_mul_f32 v[30:31], v[0:1], v[30:31] op_sel_hi:[0,1]
	v_pk_mul_f32 v[28:29], v[0:1], v[28:29] op_sel_hi:[0,1]
	v_pk_mul_f32 v[26:27], v[0:1], v[26:27] op_sel_hi:[0,1]
	v_pk_mul_f32 v[24:25], v[0:1], v[24:25] op_sel_hi:[0,1]
	v_pk_mul_f32 v[22:23], v[0:1], v[22:23] op_sel_hi:[0,1]
	v_pk_mul_f32 v[20:21], v[0:1], v[20:21] op_sel_hi:[0,1]
	v_pk_mul_f32 v[18:19], v[0:1], v[18:19] op_sel_hi:[0,1]
	v_pk_mul_f32 v[16:17], v[0:1], v[16:17] op_sel_hi:[0,1]
.Lav_noscale:
	ds_read_b64_tr_b16 v[240:241], v3 offset:320
	ds_read_b64_tr_b16 v[242:243], v3 offset:5568
	ds_read_b64_tr_b16 v[244:245], v3 offset:384
	ds_read_b64_tr_b16 v[246:247], v3 offset:5632
	ds_read_b64_tr_b16 v[248:249], v3 offset:448
	ds_read_b64_tr_b16 v[250:251], v3 offset:5696
	s_waitcnt lgkmcnt(14)
	v_mfma_f32_32x32x16_bf16 v[128:143], v[220:223], v[176:179], v[128:143]
	ds_read_b64_tr_b16 v[220:221], v3 offset:10496
	ds_read_b64_tr_b16 v[222:223], v3 offset:15744
	s_waitcnt lgkmcnt(14)
	v_mfma_f32_32x32x16_bf16 v[112:127], v[224:227], v[176:179], v[112:127]
	ds_read_b64_tr_b16 v[224:225], v3 offset:10560
	ds_read_b64_tr_b16 v[226:227], v3 offset:15808
	s_waitcnt lgkmcnt(14)
	v_mfma_f32_32x32x16_bf16 v[96:111], v[228:231], v[176:179], v[96:111]
	ds_read_b64_tr_b16 v[228:229], v3 offset:10624
	ds_read_b64_tr_b16 v[230:231], v3 offset:15872
	s_waitcnt lgkmcnt(14)
	v_mfma_f32_32x32x16_bf16 v[80:95], v[232:235], v[176:179], v[80:95]
	ds_read_b64_tr_b16 v[232:233], v3 offset:10688
	ds_read_b64_tr_b16 v[234:235], v3 offset:15936
	s_waitcnt lgkmcnt(14)
	v_mfma_f32_32x32x16_bf16 v[64:79], v[236:239], v[176:179], v[64:79]
	ds_read_b64_tr_b16 v[236:237], v3 offset:10752
	ds_read_b64_tr_b16 v[238:239], v3 offset:16000
	s_waitcnt lgkmcnt(14)
	v_mfma_f32_32x32x16_bf16 v[48:63], v[240:243], v[176:179], v[48:63]
	ds_read_b64_tr_b16 v[240:241], v3 offset:10816
	ds_read_b64_tr_b16 v[242:243], v3 offset:16064
	s_waitcnt lgkmcnt(14)
	v_mfma_f32_32x32x16_bf16 v[32:47], v[244:247], v[176:179], v[32:47]
	ds_read_b64_tr_b16 v[244:245], v3 offset:10880
	ds_read_b64_tr_b16 v[246:247], v3 offset:16128
	s_waitcnt lgkmcnt(14)
	v_mfma_f32_32x32x16_bf16 v[16:31], v[248:251], v[176:179], v[16:31]
	ds_read_b64_tr_b16 v[248:249], v3 offset:10944
	ds_read_b64_tr_b16 v[250:251], v3 offset:16192
	s_waitcnt lgkmcnt(14)
	v_mfma_f32_32x32x16_bf16 v[128:143], v[220:223], v[180:183], v[128:143]
	ds_read_b64_tr_b16 v[220:221], v3 offset:20992
	ds_read_b64_tr_b16 v[222:223], v3 offset:26240
	s_waitcnt lgkmcnt(14)
	v_mfma_f32_32x32x16_bf16 v[112:127], v[224:227], v[180:183], v[112:127]
	ds_read_b64_tr_b16 v[224:225], v3 offset:21056
	ds_read_b64_tr_b16 v[226:227], v3 offset:26304
	s_waitcnt lgkmcnt(14)
	v_mfma_f32_32x32x16_bf16 v[96:111], v[228:231], v[180:183], v[96:111]
	ds_read_b64_tr_b16 v[228:229], v3 offset:21120
	ds_read_b64_tr_b16 v[230:231], v3 offset:26368
	s_waitcnt lgkmcnt(14)
	v_mfma_f32_32x32x16_bf16 v[80:95], v[232:235], v[180:183], v[80:95]
	ds_read_b64_tr_b16 v[232:233], v3 offset:21184
	ds_read_b64_tr_b16 v[234:235], v3 offset:26432
	s_waitcnt lgkmcnt(14)
	v_mfma_f32_32x32x16_bf16 v[64:79], v[236:239], v[180:183], v[64:79]
	ds_read_b64_tr_b16 v[236:237], v3 offset:21248
	ds_read_b64_tr_b16 v[238:239], v3 offset:26496
	s_waitcnt lgkmcnt(14)
	v_mfma_f32_32x32x16_bf16 v[48:63], v[240:243], v[180:183], v[48:63]
	ds_read_b64_tr_b16 v[240:241], v3 offset:21312
	ds_read_b64_tr_b16 v[242:243], v3 offset:26560
	s_waitcnt lgkmcnt(14)
	v_mfma_f32_32x32x16_bf16 v[32:47], v[244:247], v[180:183], v[32:47]
	ds_read_b64_tr_b16 v[244:245], v3 offset:21376
	ds_read_b64_tr_b16 v[246:247], v3 offset:26624
	s_waitcnt lgkmcnt(14)
	v_mfma_f32_32x32x16_bf16 v[16:31], v[248:251], v[180:183], v[16:31]
	ds_read_b64_tr_b16 v[248:249], v3 offset:21440
	ds_read_b64_tr_b16 v[250:251], v3 offset:26688
	s_waitcnt vmcnt(0)
	ds_write_b128 v145, v[4:7]
	ds_write_b128 v145, v[8:11] offset:16
	ds_write_b128 v145, v[12:15] offset:32
	ds_write_b128 v145, v[146:149] offset:48
	ds_write_b128 v145, v[150:153] offset:64
	global_load_dwordx4 v[4:7], v[252:253], off offset:80
	global_load_dwordx4 v[8:11], v[252:253], off offset:96
	global_load_dwordx4 v[12:15], v[252:253], off offset:112
	global_load_dwordx4 v[146:149], v[252:253], off offset:128
	global_load_dwordx4 v[150:153], v[252:253], off offset:144
	s_waitcnt lgkmcnt(15)
	v_mfma_f32_32x32x16_bf16 v[128:143], v[220:223], v[184:187], v[128:143]
	ds_read_b64_tr_b16 v[220:221], v3 offset:31488
	ds_read_b64_tr_b16 v[222:223], v3 offset:36736
	s_waitcnt lgkmcnt(15)
	v_mfma_f32_32x32x16_bf16 v[112:127], v[224:227], v[184:187], v[112:127]
	ds_read_b64_tr_b16 v[224:225], v3 offset:31552
	ds_read_b64_tr_b16 v[226:227], v3 offset:36800
	s_waitcnt lgkmcnt(15)
	v_mfma_f32_32x32x16_bf16 v[96:111], v[228:231], v[184:187], v[96:111]
	ds_read_b64_tr_b16 v[228:229], v3 offset:31616
	ds_read_b64_tr_b16 v[230:231], v3 offset:36864
	s_waitcnt lgkmcnt(15)
	v_mfma_f32_32x32x16_bf16 v[80:95], v[232:235], v[184:187], v[80:95]
	ds_read_b64_tr_b16 v[232:233], v3 offset:31680
	ds_read_b64_tr_b16 v[234:235], v3 offset:36928
	s_waitcnt lgkmcnt(15)
	v_mfma_f32_32x32x16_bf16 v[64:79], v[236:239], v[184:187], v[64:79]
	ds_read_b64_tr_b16 v[236:237], v3 offset:31744
	ds_read_b64_tr_b16 v[238:239], v3 offset:36992
	s_waitcnt lgkmcnt(15)
	v_mfma_f32_32x32x16_bf16 v[48:63], v[240:243], v[184:187], v[48:63]
	ds_read_b64_tr_b16 v[240:241], v3 offset:31808
	ds_read_b64_tr_b16 v[242:243], v3 offset:37056
	s_waitcnt lgkmcnt(15)
	v_mfma_f32_32x32x16_bf16 v[32:47], v[244:247], v[184:187], v[32:47]
	ds_read_b64_tr_b16 v[244:245], v3 offset:31872
	ds_read_b64_tr_b16 v[246:247], v3 offset:37120
	s_waitcnt lgkmcnt(15)
	v_mfma_f32_32x32x16_bf16 v[16:31], v[248:251], v[184:187], v[16:31]
	ds_read_b64_tr_b16 v[248:249], v3 offset:31936
	ds_read_b64_tr_b16 v[250:251], v3 offset:37184
	s_waitcnt lgkmcnt(14)
	v_mfma_f32_32x32x16_bf16 v[128:143], v[220:223], v[188:191], v[128:143]
	s_waitcnt lgkmcnt(12)
	v_mfma_f32_32x32x16_bf16 v[112:127], v[224:227], v[188:191], v[112:127]
	s_waitcnt lgkmcnt(10)
	v_mfma_f32_32x32x16_bf16 v[96:111], v[228:231], v[188:191], v[96:111]
	s_waitcnt lgkmcnt(8)
	v_mfma_f32_32x32x16_bf16 v[80:95], v[232:235], v[188:191], v[80:95]
	s_waitcnt lgkmcnt(6)
	v_mfma_f32_32x32x16_bf16 v[64:79], v[236:239], v[188:191], v[64:79]
	s_waitcnt lgkmcnt(4)
	v_mfma_f32_32x32x16_bf16 v[48:63], v[240:243], v[188:191], v[48:63]
	s_waitcnt lgkmcnt(2)
	v_mfma_f32_32x32x16_bf16 v[32:47], v[244:247], v[188:191], v[32:47]
	s_waitcnt lgkmcnt(0)
	v_mfma_f32_32x32x16_bf16 v[16:31], v[248:251], v[188:191], v[16:31]
	s_waitcnt vmcnt(0)
	ds_write_b128 v145, v[4:7] offset:80
	ds_write_b128 v145, v[8:11] offset:96
	ds_write_b128 v145, v[12:15] offset:112
	ds_write_b128 v145, v[146:149] offset:128
	ds_write_b128 v145, v[150:153] offset:144
	s_mov_b64 s[8:9], 0xa000
	v_lshl_add_u64 v[252:253], v[252:253], 0, s[8:9]
	s_waitcnt lgkmcnt(0)
	s_branch .LBB0_401
.Lav_stage0:
	s_add_i32 s8, s19, 2
	s_mul_hi_u32 s9, s8, 0xaaaaaaab
	s_lshr_b32 s9, s9, 1
	s_mul_i32 s9, s9, 3
	s_sub_i32 s8, s8, s9
	s_mul_i32 s8, s8, 0xa400
	v_add_u32_e32 v145, s8, v170
	global_load_dwordx4 v[4:7], v[252:253], off
	global_load_dwordx4 v[8:11], v[252:253], off offset:16
	global_load_dwordx4 v[12:15], v[252:253], off offset:32
	global_load_dwordx4 v[146:149], v[252:253], off offset:48
	global_load_dwordx4 v[150:153], v[252:253], off offset:64
	s_waitcnt vmcnt(0)
	ds_write_b128 v145, v[4:7]
	ds_write_b128 v145, v[8:11] offset:16
	ds_write_b128 v145, v[12:15] offset:32
	ds_write_b128 v145, v[146:149] offset:48
	ds_write_b128 v145, v[150:153] offset:64
	global_load_dwordx4 v[4:7], v[252:253], off offset:80
	global_load_dwordx4 v[8:11], v[252:253], off offset:96
	global_load_dwordx4 v[12:15], v[252:253], off offset:112
	global_load_dwordx4 v[146:149], v[252:253], off offset:128
	global_load_dwordx4 v[150:153], v[252:253], off offset:144
	s_waitcnt vmcnt(0)
	ds_write_b128 v145, v[4:7] offset:80
	ds_write_b128 v145, v[8:11] offset:96
	ds_write_b128 v145, v[12:15] offset:112
	ds_write_b128 v145, v[146:149] offset:128
	ds_write_b128 v145, v[150:153] offset:144
	s_mov_b64 s[8:9], 0xa000
	v_lshl_add_u64 v[252:253], v[252:253], 0, s[8:9]
	s_waitcnt lgkmcnt(0)

.LBB0_405:
	v_add_u32_e32 v0, s29, v219
	v_mov_b64_e32 v[2:3], s[6:7]
	s_movk_i32 s8, 0x2800
	v_mad_i64_i32 v[2:3], s[8:9], v0, s8, v[2:3]
	v_or_b32_e32 v0, s28, v161
	v_mul_u32_u24_e32 v0, 0x140, v0
	v_lshlrev_b32_e32 v0, 1, v0
	v_lshl_add_u64 v[32:33], v[2:3], 0, v[0:1]
	s_setprio 2
	v_mov_b32_e32 v165, v1
	v_lshl_add_u64 v[32:33], v[32:33], 0, v[164:165]
	global_load_dwordx4 v[34:37], v[32:33], off
	global_load_dwordx4 v[38:41], v[32:33], off offset:32
	global_load_dwordx4 v[42:45], v[32:33], off offset:64
	global_load_dwordx4 v[46:49], v[32:33], off offset:96
	global_load_dwordx4 v[50:53], v[32:33], off offset:128
	global_load_dwordx4 v[54:57], v[32:33], off offset:160
	global_load_dwordx4 v[58:61], v[32:33], off offset:192
	global_load_dwordx4 v[62:65], v[32:33], off offset:224
	global_load_dwordx4 v[66:69], v[32:33], off offset:256
	global_load_dwordx4 v[70:73], v[32:33], off offset:288
	global_load_dwordx4 v[74:77], v[32:33], off offset:320
	global_load_dwordx4 v[78:81], v[32:33], off offset:352
	global_load_dwordx4 v[82:85], v[32:33], off offset:384
	global_load_dwordx4 v[86:89], v[32:33], off offset:416
	global_load_dwordx4 v[90:93], v[32:33], off offset:448
	global_load_dwordx4 v[94:97], v[32:33], off offset:480
	global_load_dwordx4 v[98:101], v[32:33], off offset:512
	global_load_dwordx4 v[102:105], v[32:33], off offset:544
	global_load_dwordx4 v[106:109], v[32:33], off offset:576
	global_load_dwordx4 v[110:113], v[32:33], off offset:608
	s_cmp_gt_i32 s27, 1
	s_cselect_b32 s8, 0xa000, 0
	s_add_u32 s8, s16, s8
	s_addc_u32 s9, s17, 0
	s_cmp_lt_i32 s27, 0
	v_mov_b32_e32 v0, 0
	s_waitcnt lgkmcnt(0)
	s_barrier
	s_cbranch_scc1 .LBB0_416
	s_mov_b64 s[8:9], 0x14090
	s_mov_b32 s18, 1
	s_add_i32 s19, s27, 1
	v_mov_b32_e32 v165, 0xf149f2ca
	v_mov_b32_e32 v0, 0
	s_mov_b32 s28, 0
	s_mov_b32 s29, 0
	s_mov_b32 s8, 0
	s_add_i32 s30, s8, 1
	s_cmp_ge_i32 s30, s27
	s_cbranch_scc1 .LBB0_409
.LBB0_407:
.LBB0_409:
	s_cmp_ge_i32 s8, s27
	s_cbranch_scc1 .LBB0_413
	s_mul_hi_u32 s8, s8, 0xaaaaaaab
	s_lshr_b32 s8, s8, 1
	s_mul_i32 s8, s8, 0xfffe1400
	s_add_i32 s8, s28, s8
	v_add_u32_e32 v175, s8, v174
	ds_read_b128 v[176:179], v175
	ds_read_b128 v[180:183], v175 offset:32
	ds_read_b128 v[184:187], v175 offset:20992
	ds_read_b128 v[188:191], v175 offset:21024
	ds_read_b128 v[220:223], v175 offset:64
	ds_read_b128 v[224:227], v175 offset:21056
	ds_read_b128 v[228:231], v175 offset:96
	ds_read_b128 v[232:235], v175 offset:21088
	ds_read_b128 v[236:239], v175 offset:128
	ds_read_b128 v[240:243], v175 offset:21120
	s_mov_b32 s8, 0xf149f2ca
	s_waitcnt vmcnt(19) lgkmcnt(9)
	v_mfma_f32_32x32x16_bf16 v[18:33], v[176:179], v[34:37], 0
	ds_read_b128 v[176:179], v175 offset:160
	s_waitcnt vmcnt(18) lgkmcnt(9)
	v_mfma_f32_32x32x16_bf16 v[18:33], v[180:183], v[38:41], v[18:33]
	ds_read_b128 v[180:183], v175 offset:21152
	s_waitcnt lgkmcnt(9)
	v_mfma_f32_32x32x16_bf16 v[2:17], v[184:187], v[34:37], 0
	ds_read_b128 v[184:187], v175 offset:192
	s_waitcnt lgkmcnt(9)
	v_mfma_f32_32x32x16_bf16 v[2:17], v[188:191], v[38:41], v[2:17]
	ds_read_b128 v[188:191], v175 offset:21184
	s_waitcnt vmcnt(17) lgkmcnt(9)
	v_mfma_f32_32x32x16_bf16 v[18:33], v[220:223], v[42:45], v[18:33]
	ds_read_b128 v[220:223], v175 offset:224
	s_waitcnt lgkmcnt(9)
	v_mfma_f32_32x32x16_bf16 v[2:17], v[224:227], v[42:45], v[2:17]
	ds_read_b128 v[224:227], v175 offset:21216
	s_waitcnt vmcnt(16) lgkmcnt(9)
	v_mfma_f32_32x32x16_bf16 v[18:33], v[228:231], v[46:49], v[18:33]
	ds_read_b128 v[228:231], v175 offset:256
	s_waitcnt lgkmcnt(9)
	v_mfma_f32_32x32x16_bf16 v[2:17], v[232:235], v[46:49], v[2:17]
	ds_read_b128 v[232:235], v175 offset:21248
	s_waitcnt vmcnt(15) lgkmcnt(9)
	v_mfma_f32_32x32x16_bf16 v[18:33], v[236:239], v[50:53], v[18:33]
	ds_read_b128 v[236:239], v175 offset:288
	s_waitcnt lgkmcnt(9)
	v_mfma_f32_32x32x16_bf16 v[2:17], v[240:243], v[50:53], v[2:17]
	ds_read_b128 v[240:243], v175 offset:21280
	s_waitcnt vmcnt(14) lgkmcnt(9)
	v_mfma_f32_32x32x16_bf16 v[18:33], v[176:179], v[54:57], v[18:33]
	ds_read_b128 v[176:179], v175 offset:320
	s_waitcnt lgkmcnt(9)
	v_mfma_f32_32x32x16_bf16 v[2:17], v[180:183], v[54:57], v[2:17]
	ds_read_b128 v[180:183], v175 offset:21312
	s_waitcnt vmcnt(13) lgkmcnt(9)
	v_mfma_f32_32x32x16_bf16 v[18:33], v[184:187], v[58:61], v[18:33]
	ds_read_b128 v[184:187], v175 offset:352
	s_waitcnt lgkmcnt(9)
	v_mfma_f32_32x32x16_bf16 v[2:17], v[188:191], v[58:61], v[2:17]
	ds_read_b128 v[188:191], v175 offset:21344
	s_waitcnt vmcnt(12) lgkmcnt(9)
	v_mfma_f32_32x32x16_bf16 v[18:33], v[220:223], v[62:65], v[18:33]
	ds_read_b128 v[220:223], v175 offset:384
	s_waitcnt lgkmcnt(9)
	v_mfma_f32_32x32x16_bf16 v[2:17], v[224:227], v[62:65], v[2:17]
	ds_read_b128 v[224:227], v175 offset:21376
	s_waitcnt vmcnt(11) lgkmcnt(9)
	v_mfma_f32_32x32x16_bf16 v[18:33], v[228:231], v[66:69], v[18:33]
	ds_read_b128 v[228:231], v175 offset:416
	s_waitcnt lgkmcnt(9)
	v_mfma_f32_32x32x16_bf16 v[2:17], v[232:235], v[66:69], v[2:17]
	ds_read_b128 v[232:235], v175 offset:21408
	s_waitcnt vmcnt(10) lgkmcnt(9)
	v_mfma_f32_32x32x16_bf16 v[18:33], v[236:239], v[70:73], v[18:33]
	ds_read_b128 v[236:239], v175 offset:448
	s_waitcnt lgkmcnt(9)
	v_mfma_f32_32x32x16_bf16 v[2:17], v[240:243], v[70:73], v[2:17]
	ds_read_b128 v[240:243], v175 offset:21440
	s_waitcnt vmcnt(9) lgkmcnt(9)
	v_mfma_f32_32x32x16_bf16 v[18:33], v[176:179], v[74:77], v[18:33]
	ds_read_b128 v[176:179], v175 offset:480
	s_waitcnt lgkmcnt(9)
	v_mfma_f32_32x32x16_bf16 v[2:17], v[180:183], v[74:77], v[2:17]
	ds_read_b128 v[180:183], v175 offset:21472
	s_waitcnt vmcnt(8) lgkmcnt(9)
	v_mfma_f32_32x32x16_bf16 v[18:33], v[184:187], v[78:81], v[18:33]
	ds_read_b128 v[184:187], v175 offset:512
	s_waitcnt lgkmcnt(9)
	v_mfma_f32_32x32x16_bf16 v[2:17], v[188:191], v[78:81], v[2:17]
	ds_read_b128 v[188:191], v175 offset:21504
	s_waitcnt vmcnt(7) lgkmcnt(9)
	v_mfma_f32_32x32x16_bf16 v[18:33], v[220:223], v[82:85], v[18:33]
	ds_read_b128 v[220:223], v175 offset:544
	s_waitcnt lgkmcnt(9)
	v_mfma_f32_32x32x16_bf16 v[2:17], v[224:227], v[82:85], v[2:17]
	ds_read_b128 v[224:227], v175 offset:21536
	s_waitcnt vmcnt(6) lgkmcnt(9)
	v_mfma_f32_32x32x16_bf16 v[18:33], v[228:231], v[86:89], v[18:33]
	ds_read_b128 v[228:231], v175 offset:576
	s_waitcnt lgkmcnt(9)
	v_mfma_f32_32x32x16_bf16 v[2:17], v[232:235], v[86:89], v[2:17]
	ds_read_b128 v[232:235], v175 offset:608
	s_waitcnt vmcnt(5) lgkmcnt(9)
	v_mfma_f32_32x32x16_bf16 v[18:33], v[236:239], v[90:93], v[18:33]
	ds_read_b128 v[236:239], v175 offset:21568
	s_waitcnt lgkmcnt(9)
	v_mfma_f32_32x32x16_bf16 v[2:17], v[240:243], v[90:93], v[2:17]
	ds_read_b128 v[240:243], v175 offset:21600
	s_waitcnt vmcnt(4) lgkmcnt(9)
	v_mfma_f32_32x32x16_bf16 v[18:33], v[176:179], v[94:97], v[18:33]
	s_waitcnt lgkmcnt(8)
	v_mfma_f32_32x32x16_bf16 v[2:17], v[180:183], v[94:97], v[2:17]
	s_waitcnt vmcnt(3) lgkmcnt(7)
	v_mfma_f32_32x32x16_bf16 v[18:33], v[184:187], v[98:101], v[18:33]
	s_waitcnt lgkmcnt(6)
	v_mfma_f32_32x32x16_bf16 v[2:17], v[188:191], v[98:101], v[2:17]
	s_waitcnt vmcnt(2) lgkmcnt(5)
	v_mfma_f32_32x32x16_bf16 v[18:33], v[220:223], v[102:105], v[18:33]
	s_waitcnt lgkmcnt(4)
	v_mfma_f32_32x32x16_bf16 v[2:17], v[224:227], v[102:105], v[2:17]
	s_waitcnt vmcnt(1) lgkmcnt(3)
	v_mfma_f32_32x32x16_bf16 v[18:33], v[228:231], v[106:109], v[18:33]
	s_waitcnt vmcnt(0) lgkmcnt(2)
	v_mfma_f32_32x32x16_bf16 v[18:33], v[232:235], v[110:113], v[18:33]
	s_waitcnt lgkmcnt(1)
	v_mfma_f32_32x32x16_bf16 v[2:17], v[236:239], v[106:109], v[2:17]
	s_nop 9
	v_max3_f32 v175, v18, s8, v19
	v_max3_f32 v175, v175, v20, v21
	v_max3_f32 v175, v175, v22, v23
	v_max3_f32 v175, v175, v24, v25
	v_max3_f32 v175, v175, v26, v27
	v_max3_f32 v175, v175, v28, v29
	v_max3_f32 v175, v175, v30, v31
	s_waitcnt lgkmcnt(0)
	v_mfma_f32_32x32x16_bf16 v[2:17], v[240:243], v[110:113], v[2:17]
	v_max3_f32 v175, v175, v32, v33
	v_xor_b32_e32 v176, 32, v192
	v_add_u32_e32 v177, 64, v193
	v_cmp_lt_i32_e32 vcc, v176, v177
	s_and_b32 s8, s29, 4
	s_or_b32 s8, s8, s91
	v_cndmask_b32_e32 v176, v192, v176, vcc
	s_nop 4
	v_max3_f32 v175, v175, v2, v3
	v_max3_f32 v175, v175, v4, v5
	v_max3_f32 v175, v175, v6, v7
	v_max3_f32 v175, v175, v8, v9
	v_max3_f32 v175, v175, v10, v11
	v_max3_f32 v175, v175, v12, v13
	v_max3_f32 v175, v175, v14, v15
	v_max3_f32 v175, v175, v16, v17
	v_lshlrev_b32_e32 v176, 2, v176
	ds_bpermute_b32 v177, v176, v175
	s_mulk_i32 s8, 0x1080
	s_add_i32 s8, s8, 0
	s_add_i32 s8, s8, 0x1ec00
	s_waitcnt lgkmcnt(0)
	v_max3_f32 v175, v165, v175, v177
	v_sub_f32_e32 v177, v175, v165
	v_cmp_lt_f32_e32 vcc, 8.0, v177
	s_nop 1
	v_cndmask_b32_e32 v175, v165, v175, vcc
	v_sub_f32_e32 v18, v18, v175
	v_exp_f32_e32 v18, v18
	v_sub_f32_e32 v19, v19, v175
	v_exp_f32_e32 v19, v19
	v_sub_f32_e32 v20, v20, v175
	v_exp_f32_e32 v20, v20
	v_sub_f32_e32 v21, v21, v175
	v_exp_f32_e32 v21, v21
	v_sub_f32_e32 v22, v22, v175
	v_add_f32_e32 v177, 0, v18
	v_exp_f32_e32 v22, v22
	v_sub_f32_e32 v23, v23, v175
	v_add_f32_e32 v177, v177, v19
	v_exp_f32_e32 v23, v23
	v_sub_f32_e32 v24, v24, v175
	v_add_f32_e32 v177, v177, v20
	v_exp_f32_e32 v24, v24
	v_sub_f32_e32 v25, v25, v175
	v_add_f32_e32 v177, v177, v21
	v_exp_f32_e32 v25, v25
	v_sub_f32_e32 v26, v26, v175
	v_add_f32_e32 v177, v177, v22
	v_exp_f32_e32 v26, v26
	v_sub_f32_e32 v27, v27, v175
	v_add_f32_e32 v177, v177, v23
	v_exp_f32_e32 v27, v27
	v_sub_f32_e32 v28, v28, v175
	v_add_f32_e32 v177, v177, v24
	v_exp_f32_e32 v28, v28
	v_sub_f32_e32 v29, v29, v175
	v_add_f32_e32 v177, v177, v25
	v_exp_f32_e32 v29, v29
	v_sub_f32_e32 v30, v30, v175
	v_add_f32_e32 v177, v177, v26
	v_exp_f32_e32 v30, v30
	v_sub_f32_e32 v31, v31, v175
	v_add_f32_e32 v177, v177, v27
	v_exp_f32_e32 v31, v31
	v_sub_f32_e32 v32, v32, v175
	v_add_f32_e32 v177, v177, v28
	v_exp_f32_e32 v32, v32
	v_sub_f32_e32 v33, v33, v175
	v_add_f32_e32 v177, v177, v29
	v_exp_f32_e32 v33, v33
	v_sub_f32_e32 v2, v2, v175
	v_add_f32_e32 v177, v177, v30
	v_exp_f32_e32 v178, v2
	v_sub_f32_e32 v2, v3, v175
	v_add_f32_e32 v177, v177, v31
	v_exp_f32_e32 v179, v2
	v_sub_f32_e32 v2, v4, v175
	v_add_f32_e32 v177, v177, v32
	v_exp_f32_e32 v180, v2
	v_sub_f32_e32 v2, v5, v175
	v_add_f32_e32 v177, v177, v33
	v_exp_f32_e32 v5, v2
	v_sub_f32_e32 v3, v6, v175
	v_add_f32_e32 v2, v177, v178
	v_exp_f32_e32 v177, v3
	v_sub_f32_e32 v3, v7, v175
	v_add_f32_e32 v2, v2, v179
	v_exp_f32_e32 v181, v3
	v_sub_f32_e32 v3, v8, v175
	v_add_f32_e32 v2, v2, v180
	v_exp_f32_e32 v182, v3
	v_sub_f32_e32 v3, v9, v175
	v_add_f32_e32 v2, v2, v5
	v_exp_f32_e32 v183, v3
	v_sub_f32_e32 v3, v10, v175
	v_add_f32_e32 v2, v2, v177
	v_exp_f32_e32 v10, v3
	v_sub_f32_e32 v3, v11, v175
	v_add_f32_e32 v2, v2, v181
	v_exp_f32_e32 v11, v3
	v_sub_f32_e32 v3, v12, v175
	v_add_f32_e32 v2, v2, v182
	v_exp_f32_e32 v12, v3
	v_sub_f32_e32 v3, v13, v175
	v_add_f32_e32 v2, v2, v183
	v_exp_f32_e32 v13, v3
	v_sub_f32_e32 v3, v14, v175
	v_add_f32_e32 v2, v2, v10
	v_exp_f32_e32 v14, v3
	v_sub_f32_e32 v3, v15, v175
	v_add_f32_e32 v2, v2, v11
	v_exp_f32_e32 v15, v3
	v_sub_f32_e32 v3, v16, v175
	v_add_f32_e32 v2, v2, v12
	v_exp_f32_e32 v16, v3
	v_sub_f32_e32 v3, v17, v175
	v_add_f32_e32 v2, v2, v13
	v_exp_f32_e32 v17, v3
	v_add_f32_e32 v2, v2, v14
	v_add_f32_e32 v2, v2, v15
	v_add_f32_e32 v2, v2, v16
	v_add_f32_e32 v2, v2, v17
	v_sub_f32_e32 v165, v165, v175
	ds_bpermute_b32 v4, v176, v2
	v_exp_f32_e32 v3, v165
	v_add_u32_e32 v165, s8, v169
	v_cvt_pk_bf16_f32 v6, v18, v19
	v_cvt_pk_bf16_f32 v7, v20, v21
	v_cvt_pk_bf16_f32 v8, v22, v23
	v_cvt_pk_bf16_f32 v9, v24, v25
	ds_write_b128 v165, v[6:9]
	v_cvt_pk_bf16_f32 v6, v26, v27
	v_cvt_pk_bf16_f32 v7, v28, v29
	v_cvt_pk_bf16_f32 v8, v30, v31
	v_cvt_pk_bf16_f32 v9, v32, v33
	ds_write_b128 v165, v[6:9] offset:1024
	v_cvt_pk_bf16_f32 v6, v178, v179
	v_cvt_pk_bf16_f32 v7, v180, v5
	v_cvt_pk_bf16_f32 v8, v177, v181
	v_cvt_pk_bf16_f32 v9, v182, v183
	ds_write_b128 v165, v[6:9] offset:2048
	v_cvt_pk_bf16_f32 v6, v10, v11
	v_cvt_pk_bf16_f32 v7, v12, v13
	v_cvt_pk_bf16_f32 v8, v14, v15
	v_cvt_pk_bf16_f32 v9, v16, v17
	ds_write_b128 v165, v[6:9] offset:3072
	s_and_saveexec_b64 s[16:17], s[4:5]
	v_add_u32_e32 v5, s8, v171
	ds_write_b32 v5, v3 offset:4096
	s_or_b64 exec, exec, s[16:17]
	s_waitcnt lgkmcnt(4)
	v_add_f32_e32 v2, v2, v4
	v_fmac_f32_e32 v2, v0, v3
	v_mov_b32_e32 v0, v2
	s_branch .LBB0_414
